# in-layer weight-conversion loops (proj rd5 / merge / out idle workgroups): the four tile loads issued together with counted vmcnt waits instead of four serialised load-wait-LDS-write steps
# speedup vs baseline: 1.0878x; 1.0126x over previous
.LBB0_154:
	v_mov_b32_e32 v1, v193
	v_lshl_add_u64 v[14:15], v[14:15], 0, v[0:1]
	v_mul_u32_u24_e32 v1, v16, v18
	v_lshlrev_b32_e32 v192, 2, v1
	v_lshl_add_u64 v[32:33], v[14:15], 0, v[192:193]
	global_load_dwordx4 v[32:35], v[32:33], off
	v_mul_u32_u24_e32 v1, v16, v19
	v_lshlrev_b32_e32 v192, 2, v1
	v_lshl_add_u64 v[36:37], v[14:15], 0, v[192:193]
	global_load_dwordx4 v[36:39], v[36:37], off
	v_mul_u32_u24_e32 v1, v16, v20
	v_lshlrev_b32_e32 v192, 2, v1
	v_lshl_add_u64 v[40:41], v[14:15], 0, v[192:193]
	global_load_dwordx4 v[40:43], v[40:41], off
	v_mul_u32_u24_e32 v1, v16, v21
	v_lshlrev_b32_e32 v192, 2, v1
	v_lshl_add_u64 v[14:15], v[14:15], 0, v[192:193]
	global_load_dwordx4 v[14:17], v[14:15], off
	s_waitcnt vmcnt(3)
	ds_write2_b32 v24, v32, v33 offset1:1
	ds_write2_b32 v24, v34, v35 offset0:2 offset1:3
	s_waitcnt vmcnt(2)
	ds_write2_b32 v25, v36, v37 offset1:1
	ds_write2_b32 v26, v38, v39 offset1:1
	s_waitcnt vmcnt(1)
	ds_write2_b32 v27, v40, v41 offset1:1
	ds_write2_b32 v28, v42, v43 offset1:1
	s_waitcnt vmcnt(0)
	ds_write2_b32 v29, v14, v15 offset1:1
	ds_write2_b32 v30, v16, v17 offset1:1

.LBB0_417:
	v_mov_b32_e32 v1, v193
	v_lshl_add_u64 v[8:9], v[8:9], 0, v[0:1]
	v_mul_u32_u24_e32 v1, v10, v14
	v_lshlrev_b32_e32 v192, 2, v1
	v_lshl_add_u64 v[22:23], v[8:9], 0, v[192:193]
	global_load_dwordx4 v[22:25], v[22:23], off
	v_mul_u32_u24_e32 v1, v10, v15
	v_lshlrev_b32_e32 v192, 2, v1
	v_lshl_add_u64 v[26:27], v[8:9], 0, v[192:193]
	global_load_dwordx4 v[26:29], v[26:27], off
	v_mul_u32_u24_e32 v1, v10, v16
	v_lshlrev_b32_e32 v192, 2, v1
	v_lshl_add_u64 v[30:31], v[8:9], 0, v[192:193]
	global_load_dwordx4 v[30:33], v[30:31], off
	v_mul_u32_u24_e32 v1, v10, v17
	v_lshlrev_b32_e32 v192, 2, v1
	v_lshl_add_u64 v[8:9], v[8:9], 0, v[192:193]
	global_load_dwordx4 v[8:11], v[8:9], off
	s_waitcnt vmcnt(3)
	ds_write2_b32 v21, v22, v23 offset1:1
	ds_write2_b32 v21, v24, v25 offset0:2 offset1:3
	s_waitcnt vmcnt(2)
	v_add_u32_e32 v1, 0x1040, v21
	ds_write2_b32 v1, v26, v27 offset1:1
	v_add_u32_e32 v1, 0x1048, v21
	ds_write2_b32 v1, v28, v29 offset1:1
	s_waitcnt vmcnt(1)
	v_add_u32_e32 v1, 0x2080, v21
	ds_write2_b32 v1, v30, v31 offset1:1
	v_add_u32_e32 v1, 0x2088, v21
	ds_write2_b32 v1, v32, v33 offset1:1
	s_waitcnt vmcnt(0)
	v_add_u32_e32 v1, 0x30c0, v21
	ds_write2_b32 v1, v8, v9 offset1:1
	v_add_u32_e32 v1, 0x30c8, v21
	ds_write2_b32 v1, v10, v11 offset1:1

.LBB0_501:
	v_mov_b32_e32 v1, v193
	v_lshl_add_u64 v[8:9], v[8:9], 0, v[0:1]
	v_mul_u32_u24_e32 v1, v10, v13
	v_lshlrev_b32_e32 v192, 2, v1
	v_lshl_add_u64 v[22:23], v[8:9], 0, v[192:193]
	global_load_dwordx4 v[22:25], v[22:23], off
	v_mul_u32_u24_e32 v1, v10, v14
	v_lshlrev_b32_e32 v192, 2, v1
	v_lshl_add_u64 v[26:27], v[8:9], 0, v[192:193]
	global_load_dwordx4 v[26:29], v[26:27], off
	v_mul_u32_u24_e32 v1, v10, v15
	v_lshlrev_b32_e32 v192, 2, v1
	v_lshl_add_u64 v[30:31], v[8:9], 0, v[192:193]
	global_load_dwordx4 v[30:33], v[30:31], off
	v_mul_u32_u24_e32 v1, v10, v16
	v_lshlrev_b32_e32 v192, 2, v1
	v_lshl_add_u64 v[8:9], v[8:9], 0, v[192:193]
	global_load_dwordx4 v[8:11], v[8:9], off
	s_waitcnt vmcnt(3)
	ds_write2_b32 v20, v22, v23 offset1:1
	ds_write2_b32 v20, v24, v25 offset0:2 offset1:3
	s_waitcnt vmcnt(2)
	v_add_u32_e32 v1, 0x1040, v20
	ds_write2_b32 v1, v26, v27 offset1:1
	v_add_u32_e32 v1, 0x1048, v20
	ds_write2_b32 v1, v28, v29 offset1:1
	s_waitcnt vmcnt(1)
	v_add_u32_e32 v1, 0x2080, v20
	ds_write2_b32 v1, v30, v31 offset1:1
	v_add_u32_e32 v1, 0x2088, v20
	ds_write2_b32 v1, v32, v33 offset1:1
	s_waitcnt vmcnt(0)
	v_add_u32_e32 v1, 0x30c0, v20
	ds_write2_b32 v1, v8, v9 offset1:1
	v_add_u32_e32 v1, 0x30c8, v20
	ds_write2_b32 v1, v10, v11 offset1:1
